# attention: last P.V block's V reads issued in pairs behind each MFMA of the previous P.V block (fragment registers reused as soon as read), so little LDS latency is left in front of the barrier
# speedup vs baseline: 1.0026x; 1.0026x over previous
.LBB0_1031:
	s_lshl_b32 s0, s75, 13
	s_add_i32 s77, s0, 0
	s_setprio 1
	v_add_u32_e32 v112, s77, v189
	v_add_u32_e32 v68, v112, v191
	ds_read_b128 v[64:67], v68 offset:49152
	ds_read_b128 v[68:71], v68 offset:53248
	v_add_u32_e32 v113, v112, v192
	ds_read_b128 v[220:223], v113 offset:49152
	ds_read_b128 v[224:227], v113 offset:53248
	v_add_u32_e32 v113, v112, v193
	s_waitcnt lgkmcnt(0)
	v_mfma_f32_32x32x16_bf16 v[80:95], v[64:67], v[108:111], 0
	v_add_u32_e32 v112, v112, v194
	v_mfma_f32_32x32x16_bf16 v[64:79], v[68:71], v[108:111], 0
	v_mfma_f32_32x32x16_bf16 v[80:95], v[220:223], v[104:107], v[80:95]
	v_mfma_f32_32x32x16_bf16 v[64:79], v[224:227], v[104:107], v[64:79]
	ds_read_b128 v[220:223], v113 offset:49152
	ds_read_b128 v[224:227], v113 offset:53248
	s_waitcnt lgkmcnt(0)
	v_mfma_f32_32x32x16_bf16 v[80:95], v[220:223], v[100:103], v[80:95]
	v_mfma_f32_32x32x16_bf16 v[64:79], v[224:227], v[100:103], v[64:79]
	ds_read_b128 v[220:223], v112 offset:49152
	ds_read_b128 v[224:227], v112 offset:53248
	s_waitcnt lgkmcnt(0)
	v_mfma_f32_32x32x16_bf16 v[80:95], v[220:223], v[96:99], v[80:95]
	v_mfma_f32_32x32x16_bf16 v[64:79], v[224:227], v[96:99], v[64:79]
	s_setprio 0
	v_exp_f32_e32 v174, v174
	v_exp_f32_e32 v175, v175
	v_add_f32_e32 v112, v115, v174
	v_add_f32_e32 v113, v124, v175
	v_exp_f32_e32 v172, v172
	v_add_f32_e32 v112, v112, v125
	v_add_f32_e32 v113, v113, v126
	v_exp_f32_e32 v173, v173
	v_add_f32_e32 v112, v112, v172
	v_add_f32_e32 v113, v113, v173
	v_exp_f32_e32 v170, v170
	v_add_f32_e32 v112, v112, v127
	v_add_f32_e32 v113, v113, v176
	v_exp_f32_e32 v171, v171
	v_add_f32_e32 v112, v112, v170
	v_add_f32_e32 v113, v113, v171
	v_exp_f32_e32 v168, v168
	v_add_f32_e32 v112, v112, v177
	v_add_f32_e32 v113, v113, v178
	v_exp_f32_e32 v169, v169
	v_add_f32_e32 v112, v112, v168
	v_add_f32_e32 v113, v113, v169
	v_exp_f32_e32 v166, v166
	v_add_f32_e32 v112, v112, v116
	v_add_f32_e32 v113, v113, v117
	v_exp_f32_e32 v167, v167
	v_add_f32_e32 v112, v112, v166
	v_add_f32_e32 v113, v113, v167
	v_exp_f32_e32 v164, v164
	v_add_f32_e32 v112, v112, v118
	v_add_f32_e32 v113, v113, v119
	v_exp_f32_e32 v165, v165
	v_add_f32_e32 v112, v112, v164
	v_add_f32_e32 v113, v113, v165
	v_exp_f32_e32 v162, v162
	v_add_f32_e32 v112, v112, v120
	v_add_f32_e32 v113, v113, v121
	v_exp_f32_e32 v163, v163
	v_exp_f32_e32 v160, v160
	v_exp_f32_e32 v161, v161
	v_add_f32_e32 v112, v112, v162
	v_add_f32_e32 v113, v113, v163
	s_nop 0
	v_add_f32_e32 v112, v112, v122
	v_add_f32_e32 v113, v113, v123
	s_nop 0
	v_add_f32_e32 v112, v112, v160
	v_add_f32_e32 v113, v113, v161
	s_nop 0
	v_add_f32_e32 v219, v112, v113
	v_cvt_pk_bf16_f32 v112, v115, v124
	v_cvt_pk_bf16_f32 v113, v125, v126
	v_cvt_pk_bf16_f32 v114, v127, v176
	v_cvt_pk_bf16_f32 v115, v177, v178
	v_cvt_pk_bf16_f32 v116, v116, v117
	s_nop 0
	v_mov_b32_e32 v220, v219
	s_nop 1
	v_permlane32_swap_b32_e32 v219, v220
	v_cvt_pk_bf16_f32 v117, v118, v119
	v_cvt_pk_bf16_f32 v118, v120, v121
	v_cvt_pk_bf16_f32 v119, v122, v123
	v_cvt_pk_bf16_f32 v120, v174, v175
	v_cvt_pk_bf16_f32 v121, v172, v173
	v_cvt_pk_bf16_f32 v122, v170, v171
	v_cvt_pk_bf16_f32 v123, v168, v169
	v_cvt_pk_bf16_f32 v124, v166, v167
	v_cvt_pk_bf16_f32 v125, v164, v165
	v_cvt_pk_bf16_f32 v126, v162, v163
	v_cvt_pk_bf16_f32 v127, v160, v161
	v_permlane32_swap_b32_e32 v112, v114
	v_permlane32_swap_b32_e32 v113, v115
	v_permlane32_swap_b32_e32 v116, v118
	v_permlane32_swap_b32_e32 v117, v119
	v_permlane32_swap_b32_e32 v120, v122
	v_permlane32_swap_b32_e32 v121, v123
	v_permlane32_swap_b32_e32 v124, v126
	v_permlane32_swap_b32_e32 v125, v127
	s_lshl_b32 s0, s76, 14
	v_add_u32_e32 v176, s0, v187
	ds_read_b64_tr_b16 v[160:161], v176 offset:0
	ds_read_b64_tr_b16 v[162:163], v176 offset:0x800
	ds_read_b64_tr_b16 v[164:165], v176 offset:0x1000
	ds_read_b64_tr_b16 v[166:167], v176 offset:0x1800
	ds_read_b64_tr_b16 v[168:169], v176 offset:0x2000
	ds_read_b64_tr_b16 v[170:171], v176 offset:0x2800
	ds_read_b64_tr_b16 v[172:173], v176 offset:0x3000
	ds_read_b64_tr_b16 v[174:175], v176 offset:0x3800
	s_setprio 1
	s_waitcnt lgkmcnt(6)
	v_mfma_f32_32x32x16_bf16 v[48:63], v[112:115], v[160:163], v[48:63]
	s_waitcnt lgkmcnt(4)
	v_mfma_f32_32x32x16_bf16 v[48:63], v[116:119], v[164:167], v[48:63]
	s_waitcnt lgkmcnt(2)
	v_mfma_f32_32x32x16_bf16 v[48:63], v[120:123], v[168:171], v[48:63]
	s_waitcnt lgkmcnt(0)
	v_mfma_f32_32x32x16_bf16 v[48:63], v[124:127], v[172:175], v[48:63]
	s_setprio 0
	v_max3_f32 v160, v80, v81, v82
	v_max3_f32 v161, v64, v65, v66
	v_max_f32_e32 v162, v79, v79
	v_max3_f32 v160, v160, v83, v84
	v_max3_f32 v161, v161, v67, v68
	v_max_f32_e32 v163, v95, v95
	v_max3_f32 v160, v160, v85, v86
	v_max3_f32 v161, v161, v69, v70
	v_max_f32_e32 v162, v163, v162
	v_max3_f32 v160, v160, v87, v88
	v_max3_f32 v161, v161, v71, v72
	s_nop 0
	v_max3_f32 v160, v160, v89, v90
	v_max3_f32 v161, v161, v73, v74
	s_nop 0
	v_max3_f32 v160, v160, v91, v92
	v_max3_f32 v161, v161, v75, v76
	s_nop 0
	v_max3_f32 v160, v160, v93, v94
	v_max3_f32 v161, v161, v77, v78
	s_nop 0
	v_max3_f32 v160, v160, v161, v162
	s_nop 0
	v_mov_b32_e32 v161, v160
	s_nop 1
	v_permlane32_swap_b32_e32 v160, v161
	v_max_f32_e32 v161, v161, v161
	v_max_f32_e32 v160, v160, v160
	v_max_f32_e32 v177, v160, v161
	ds_read_b64_tr_b16 v[160:161], v176 offset:0x200
	ds_read_b64_tr_b16 v[162:163], v176 offset:0xa00
	ds_read_b64_tr_b16 v[164:165], v176 offset:0x1200
	ds_read_b64_tr_b16 v[166:167], v176 offset:0x1a00
	ds_read_b64_tr_b16 v[168:169], v176 offset:0x2200
	ds_read_b64_tr_b16 v[170:171], v176 offset:0x2a00
	ds_read_b64_tr_b16 v[172:173], v176 offset:0x3200
	ds_read_b64_tr_b16 v[174:175], v176 offset:0x3a00
	s_setprio 1
	s_waitcnt lgkmcnt(6)
	v_mfma_f32_32x32x16_bf16 v[32:47], v[112:115], v[160:163], v[32:47]
	s_waitcnt lgkmcnt(4)
	v_mfma_f32_32x32x16_bf16 v[32:47], v[116:119], v[164:167], v[32:47]
	s_waitcnt lgkmcnt(2)
	v_mfma_f32_32x32x16_bf16 v[32:47], v[120:123], v[168:171], v[32:47]
	s_waitcnt lgkmcnt(0)
	v_mfma_f32_32x32x16_bf16 v[32:47], v[124:127], v[172:175], v[32:47]
	s_setprio 0
	v_sub_f32_e32 v160, v177, v218
	v_cmp_ge_f32_e32 vcc, s71, v160
	v_max_f32_e32 v160, v218, v218
	v_max_f32_e32 v160, v160, v177
	v_sub_f32_e32 v161, v218, v160
	v_mul_f32_e32 v161, 0x3e38aa3b, v161
	v_exp_f32_e32 v161, v161
	s_cmp_eq_u64 vcc, exec
	s_cselect_b64 vcc, -1, 0
	v_cndmask_b32_e32 v222, v160, v218, vcc
	v_cndmask_b32_e64 v221, v161, 1.0, vcc
	v_mul_f32_e32 v175, 0xbe38aa3b, v222
	v_fma_f32 v80, v80, v197, v175
	v_fma_f32 v81, v81, v197, v175
	v_fma_f32 v82, v82, v197, v175
	v_fma_f32 v83, v83, v197, v175
	v_fma_f32 v84, v84, v197, v175
	v_fma_f32 v85, v85, v197, v175
	v_fma_f32 v86, v86, v197, v175
	v_fma_f32 v87, v87, v197, v175
	v_fma_f32 v88, v88, v197, v175
	v_fma_f32 v89, v89, v197, v175
	v_fma_f32 v90, v90, v197, v175
	v_fma_f32 v91, v91, v197, v175
	v_fma_f32 v92, v92, v197, v175
	v_fma_f32 v93, v93, v197, v175
	v_fma_f32 v94, v94, v197, v175
	v_fma_f32 v95, v95, v197, v175
	v_fma_f32 v160, v64, v197, v175
	v_fma_f32 v161, v65, v197, v175
	v_fma_f32 v162, v66, v197, v175
	v_fma_f32 v163, v67, v197, v175
	v_fma_f32 v164, v68, v197, v175
	v_fma_f32 v165, v69, v197, v175
	v_fma_f32 v166, v70, v197, v175
	v_fma_f32 v167, v71, v197, v175
	v_fma_f32 v168, v72, v197, v175
	v_fma_f32 v169, v73, v197, v175
	v_fma_f32 v170, v74, v197, v175
	v_fma_f32 v171, v75, v197, v175
	v_fma_f32 v172, v76, v197, v175
	v_fma_f32 v173, v77, v197, v175
	v_fma_f32 v174, v78, v197, v175
	v_fma_f32 v175, v79, v197, v175
	ds_read_b64_tr_b16 v[64:65], v176 offset:0x400
	ds_read_b64_tr_b16 v[66:67], v176 offset:0xc00
	ds_read_b64_tr_b16 v[68:69], v176 offset:0x1400
	ds_read_b64_tr_b16 v[70:71], v176 offset:0x1c00
	ds_read_b64_tr_b16 v[72:73], v176 offset:0x2400
	ds_read_b64_tr_b16 v[74:75], v176 offset:0x2c00
	ds_read_b64_tr_b16 v[76:77], v176 offset:0x3400
	ds_read_b64_tr_b16 v[78:79], v176 offset:0x3c00
	s_setprio 1
	s_waitcnt lgkmcnt(6)
	v_mfma_f32_32x32x16_bf16 v[16:31], v[112:115], v[64:67], v[16:31]
	ds_read_b64_tr_b16 v[64:65], v176 offset:0x600
	ds_read_b64_tr_b16 v[66:67], v176 offset:0xe00
	s_waitcnt lgkmcnt(6)
	v_mfma_f32_32x32x16_bf16 v[16:31], v[116:119], v[68:71], v[16:31]
	ds_read_b64_tr_b16 v[68:69], v176 offset:0x1600
	ds_read_b64_tr_b16 v[70:71], v176 offset:0x1e00
	s_waitcnt lgkmcnt(6)
	v_mfma_f32_32x32x16_bf16 v[16:31], v[120:123], v[72:75], v[16:31]
	ds_read_b64_tr_b16 v[72:73], v176 offset:0x2600
	ds_read_b64_tr_b16 v[74:75], v176 offset:0x2e00
	s_waitcnt lgkmcnt(6)
	v_mfma_f32_32x32x16_bf16 v[16:31], v[124:127], v[76:79], v[16:31]
	ds_read_b64_tr_b16 v[76:77], v176 offset:0x3600
	ds_read_b64_tr_b16 v[78:79], v176 offset:0x3e00
	s_setprio 0
	s_setprio 0
	s_lshl_b32 s1, s76, 13
	v_lshl_add_u64 v[176:177], s[46:47], 0, v[154:155]
	s_mov_b64 s[48:49], 0x14210800
	s_add_i32 s1, s51, s1
	s_waitcnt vmcnt(0) lgkmcnt(0)
	s_barrier
	s_setprio 1
	v_mfma_f32_32x32x16_bf16 v[0:15], v[112:115], v[64:67], v[0:15]
	v_lshl_add_u64 v[226:227], v[176:177], 0, s[48:49]
	s_add_i32 m0, s1, 0xc000
	v_lshl_add_u64 v[178:179], s[46:47], 0, v[156:157]
	s_add_i32 s0, s51, s0
	global_load_lds_dwordx4 v[226:227], off
	v_mfma_f32_32x32x16_bf16 v[0:15], v[116:119], v[68:71], v[0:15]
	v_lshl_add_u64 v[226:227], v[178:179], 0, s[10:11]
	s_mov_b32 m0, s0
	v_lshl_add_u64 v[180:181], s[46:47], 0, v[158:159]
	global_load_lds_dwordx4 v[226:227], off
	v_mfma_f32_32x32x16_bf16 v[0:15], v[120:123], v[72:75], v[0:15]
	v_lshl_add_u64 v[226:227], v[180:181], 0, s[10:11]
	s_add_i32 m0, s0, 0x2000
	v_cmp_gt_f32_e32 vcc, 1.0, v221
	global_load_lds_dwordx4 v[226:227], off
	v_mfma_f32_32x32x16_bf16 v[0:15], v[124:127], v[76:79], v[0:15]
	s_setprio 0
	s_cbranch_vccz .LBB0_1035
	s_and_saveexec_b64 s[0:1], s[4:5]
	ds_write_b32 v215, v221 offset:128
	s_or_b64 exec, exec, s[0:1]
	s_waitcnt lgkmcnt(0)
	v_add_u32_e32 v76, s50, v188
	ds_read_b128 v[64:67], v76 offset:224
	ds_read_b128 v[68:71], v76 offset:192
	ds_read_b128 v[72:75], v76 offset:160
	ds_read_b128 v[76:79], v76 offset:128
	s_waitcnt lgkmcnt(0)
	v_pk_mul_f32 v[60:61], v[60:61], v[64:65]
	v_pk_mul_f32 v[56:57], v[56:57], v[68:69]
	v_pk_mul_f32 v[52:53], v[52:53], v[72:73]
	v_pk_mul_f32 v[62:63], v[62:63], v[66:67]
	v_pk_mul_f32 v[58:59], v[58:59], v[70:71]
	v_pk_mul_f32 v[54:55], v[54:55], v[74:75]
	v_pk_mul_f32 v[50:51], v[50:51], v[78:79]
	v_pk_mul_f32 v[48:49], v[48:49], v[76:77]
	v_pk_mul_f32 v[44:45], v[44:45], v[64:65]
	v_pk_mul_f32 v[40:41], v[40:41], v[68:69]
	v_pk_mul_f32 v[36:37], v[36:37], v[72:73]
	v_pk_mul_f32 v[46:47], v[46:47], v[66:67]
	v_pk_mul_f32 v[42:43], v[42:43], v[70:71]
	v_pk_mul_f32 v[38:39], v[38:39], v[74:75]
	v_pk_mul_f32 v[34:35], v[34:35], v[78:79]
	v_pk_mul_f32 v[32:33], v[32:33], v[76:77]
	v_pk_mul_f32 v[28:29], v[28:29], v[64:65]
	v_pk_mul_f32 v[24:25], v[24:25], v[68:69]
	v_pk_mul_f32 v[20:21], v[20:21], v[72:73]
	v_pk_mul_f32 v[30:31], v[30:31], v[66:67]
	v_pk_mul_f32 v[26:27], v[26:27], v[70:71]
	v_pk_mul_f32 v[22:23], v[22:23], v[74:75]
	v_pk_mul_f32 v[18:19], v[18:19], v[78:79]
	v_pk_mul_f32 v[16:17], v[16:17], v[76:77]
	v_pk_mul_f32 v[12:13], v[12:13], v[64:65]
	v_pk_mul_f32 v[8:9], v[8:9], v[68:69]
	v_pk_mul_f32 v[4:5], v[4:5], v[72:73]
	v_pk_mul_f32 v[14:15], v[14:15], v[66:67]
	v_pk_mul_f32 v[10:11], v[10:11], v[70:71]
	v_pk_mul_f32 v[6:7], v[6:7], v[74:75]
	v_pk_mul_f32 v[2:3], v[2:3], v[78:79]
	v_pk_mul_f32 v[0:1], v[0:1], v[76:77]
.LBB0_1035:
	v_exp_f32_e32 v218, v88
	v_exp_f32_e32 v225, v89
	s_add_i32 s0, s75, 1
	s_cmp_lg_u32 s75, 2
	s_cselect_b32 s76, s0, 0
	v_exp_f32_e32 v120, v80
	v_exp_f32_e32 v121, v81
	v_exp_f32_e32 v122, v82
	v_exp_f32_e32 v123, v83
	v_exp_f32_e32 v124, v84
	v_exp_f32_e32 v125, v85
	v_exp_f32_e32 v126, v86
	v_exp_f32_e32 v127, v87
	v_exp_f32_e32 v226, v90
	v_exp_f32_e32 v227, v91
	v_exp_f32_e32 v228, v92
	v_exp_f32_e32 v229, v93
	v_exp_f32_e32 v230, v94
	v_exp_f32_e32 v231, v95
	s_setprio 1
	v_lshl_add_u32 v223, s76, 13, v190
	v_add_u32_e32 v68, v223, v191
	ds_read_b128 v[64:67], v68 offset:49152
	ds_read_b128 v[68:71], v68 offset:53248
	v_add_u32_e32 v116, v223, v192
	ds_read_b128 v[112:115], v116 offset:49152
	ds_read_b128 v[116:119], v116 offset:53248
	s_waitcnt lgkmcnt(0)
	v_mfma_f32_32x32x16_bf16 v[80:95], v[64:67], v[108:111], 0
	v_mfma_f32_32x32x16_bf16 v[64:79], v[68:71], v[108:111], 0
	v_mfma_f32_32x32x16_bf16 v[80:95], v[112:115], v[104:107], v[80:95]
	v_mfma_f32_32x32x16_bf16 v[64:79], v[116:119], v[104:107], v[64:79]
	v_add_u32_e32 v116, v223, v193
	ds_read_b128 v[112:115], v116 offset:49152
	ds_read_b128 v[116:119], v116 offset:53248
	s_waitcnt lgkmcnt(0)
	v_mfma_f32_32x32x16_bf16 v[80:95], v[112:115], v[100:103], v[80:95]
	v_mfma_f32_32x32x16_bf16 v[64:79], v[116:119], v[100:103], v[64:79]
	v_add_u32_e32 v116, v223, v194
	ds_read_b128 v[112:115], v116 offset:49152
	ds_read_b128 v[116:119], v116 offset:53248
	s_waitcnt lgkmcnt(0)
	v_mfma_f32_32x32x16_bf16 v[80:95], v[112:115], v[96:99], v[80:95]
	v_mfma_f32_32x32x16_bf16 v[64:79], v[116:119], v[96:99], v[64:79]
	s_setprio 0
	v_exp_f32_e32 v160, v160
	v_exp_f32_e32 v161, v161
	v_add_f32_e32 v112, v120, v160
	v_add_f32_e32 v113, v121, v161
	v_exp_f32_e32 v162, v162
	v_add_f32_e32 v112, v112, v122
	v_add_f32_e32 v113, v113, v123
	v_exp_f32_e32 v163, v163
	v_add_f32_e32 v112, v112, v162
	v_add_f32_e32 v113, v113, v163
	v_exp_f32_e32 v164, v164
	v_add_f32_e32 v112, v112, v124
	v_add_f32_e32 v113, v113, v125
	v_exp_f32_e32 v165, v165
	v_add_f32_e32 v112, v112, v164
	v_add_f32_e32 v113, v113, v165
	v_exp_f32_e32 v166, v166
	v_add_f32_e32 v112, v112, v126
	v_add_f32_e32 v113, v113, v127
	v_exp_f32_e32 v167, v167
	v_add_f32_e32 v112, v112, v166
	v_add_f32_e32 v113, v113, v167
	v_exp_f32_e32 v168, v168
	v_add_f32_e32 v112, v112, v218
	v_add_f32_e32 v113, v113, v225
	v_exp_f32_e32 v169, v169
	v_add_f32_e32 v112, v112, v168
	v_add_f32_e32 v113, v113, v169
	v_exp_f32_e32 v170, v170
	v_add_f32_e32 v112, v112, v226
	v_add_f32_e32 v113, v113, v227
	v_exp_f32_e32 v171, v171
	v_add_f32_e32 v112, v112, v170
	v_add_f32_e32 v113, v113, v171
	v_exp_f32_e32 v172, v172
	v_add_f32_e32 v112, v112, v228
	v_add_f32_e32 v113, v113, v229
	v_exp_f32_e32 v173, v173
	v_exp_f32_e32 v174, v174
	v_exp_f32_e32 v175, v175
	v_add_f32_e32 v112, v112, v172
	v_add_f32_e32 v113, v113, v173
	s_nop 0
	v_add_f32_e32 v112, v112, v230
	v_add_f32_e32 v113, v113, v231
	s_nop 0
	v_add_f32_e32 v112, v112, v174
	v_add_f32_e32 v113, v113, v175
	s_nop 0
	v_add_f32_e32 v223, v112, v113
	v_cvt_pk_bf16_f32 v112, v120, v121
	v_cvt_pk_bf16_f32 v113, v122, v123
	v_cvt_pk_bf16_f32 v114, v124, v125
	v_cvt_pk_bf16_f32 v115, v126, v127
	v_cvt_pk_bf16_f32 v116, v218, v225
	s_nop 0
	v_mov_b32_e32 v224, v223
	s_nop 1
	v_permlane32_swap_b32_e32 v223, v224
	v_cvt_pk_bf16_f32 v117, v226, v227
	v_cvt_pk_bf16_f32 v118, v228, v229
	v_cvt_pk_bf16_f32 v119, v230, v231
	v_cvt_pk_bf16_f32 v120, v160, v161
	v_cvt_pk_bf16_f32 v121, v162, v163
	v_cvt_pk_bf16_f32 v122, v164, v165
	v_cvt_pk_bf16_f32 v123, v166, v167
	v_cvt_pk_bf16_f32 v124, v168, v169
	v_cvt_pk_bf16_f32 v125, v170, v171
	v_cvt_pk_bf16_f32 v126, v172, v173
	v_cvt_pk_bf16_f32 v127, v174, v175
	v_permlane32_swap_b32_e32 v112, v114
	v_permlane32_swap_b32_e32 v113, v115
	v_permlane32_swap_b32_e32 v116, v118
	v_permlane32_swap_b32_e32 v117, v119
	v_permlane32_swap_b32_e32 v120, v122
	v_permlane32_swap_b32_e32 v121, v123
	v_permlane32_swap_b32_e32 v124, v126
	v_permlane32_swap_b32_e32 v125, v127
	s_lshl_b32 s75, s75, 14
	v_add_u32_e32 v226, s75, v187
	ds_read_b64_tr_b16 v[160:161], v226 offset:0
	ds_read_b64_tr_b16 v[162:163], v226 offset:0x800
	ds_read_b64_tr_b16 v[164:165], v226 offset:0x1000
	ds_read_b64_tr_b16 v[166:167], v226 offset:0x1800
	ds_read_b64_tr_b16 v[168:169], v226 offset:0x2000
	ds_read_b64_tr_b16 v[170:171], v226 offset:0x2800
	ds_read_b64_tr_b16 v[172:173], v226 offset:0x3000
	ds_read_b64_tr_b16 v[174:175], v226 offset:0x3800
	s_setprio 1
	s_waitcnt lgkmcnt(6)
	v_mfma_f32_32x32x16_bf16 v[48:63], v[112:115], v[160:163], v[48:63]
	s_waitcnt lgkmcnt(4)
	v_mfma_f32_32x32x16_bf16 v[48:63], v[116:119], v[164:167], v[48:63]
	s_waitcnt lgkmcnt(2)
	v_mfma_f32_32x32x16_bf16 v[48:63], v[120:123], v[168:171], v[48:63]
	s_waitcnt lgkmcnt(0)
	v_mfma_f32_32x32x16_bf16 v[48:63], v[124:127], v[172:175], v[48:63]
	s_setprio 0
	v_max3_f32 v160, v80, v81, v82
	v_max3_f32 v161, v64, v65, v66
	v_max_f32_e32 v162, v79, v79
	v_max3_f32 v160, v160, v83, v84
	v_max3_f32 v161, v161, v67, v68
	v_max_f32_e32 v163, v95, v95
	v_max3_f32 v160, v160, v85, v86
	v_max3_f32 v161, v161, v69, v70
	v_max_f32_e32 v162, v163, v162
	v_max3_f32 v160, v160, v87, v88
	v_max3_f32 v161, v161, v71, v72
	s_nop 0
	v_max3_f32 v160, v160, v89, v90
	v_max3_f32 v161, v161, v73, v74
	s_nop 0
	v_max3_f32 v160, v160, v91, v92
	v_max3_f32 v161, v161, v75, v76
	s_nop 0
	v_max3_f32 v160, v160, v93, v94
	v_max3_f32 v161, v161, v77, v78
	s_nop 0
	v_max3_f32 v160, v160, v161, v162
	s_nop 0
	v_mov_b32_e32 v161, v160
	s_nop 1
	v_permlane32_swap_b32_e32 v160, v161
	v_max_f32_e32 v161, v161, v161
	v_max_f32_e32 v160, v160, v160
	v_max_f32_e32 v218, v160, v161
	ds_read_b64_tr_b16 v[160:161], v226 offset:0x200
	ds_read_b64_tr_b16 v[162:163], v226 offset:0xa00
	ds_read_b64_tr_b16 v[164:165], v226 offset:0x1200
	ds_read_b64_tr_b16 v[166:167], v226 offset:0x1a00
	ds_read_b64_tr_b16 v[168:169], v226 offset:0x2200
	ds_read_b64_tr_b16 v[170:171], v226 offset:0x2a00
	ds_read_b64_tr_b16 v[172:173], v226 offset:0x3200
	ds_read_b64_tr_b16 v[174:175], v226 offset:0x3a00
	s_setprio 1
	s_waitcnt lgkmcnt(6)
	v_mfma_f32_32x32x16_bf16 v[32:47], v[112:115], v[160:163], v[32:47]
	s_waitcnt lgkmcnt(4)
	v_mfma_f32_32x32x16_bf16 v[32:47], v[116:119], v[164:167], v[32:47]
	s_waitcnt lgkmcnt(2)
	v_mfma_f32_32x32x16_bf16 v[32:47], v[120:123], v[168:171], v[32:47]
	s_waitcnt lgkmcnt(0)
	v_mfma_f32_32x32x16_bf16 v[32:47], v[124:127], v[172:175], v[32:47]
	s_setprio 0
	v_sub_f32_e32 v160, v218, v222
	v_cmp_ge_f32_e32 vcc, s71, v160
	s_cmp_eq_u64 vcc, exec
	v_max_f32_e32 v160, v222, v222
	v_max_f32_e32 v225, v160, v218
	s_cselect_b64 s[0:1], -1, 0
	v_cndmask_b32_e64 v218, v225, v222, s[0:1]
	v_mul_f32_e32 v161, 0xbe38aa3b, v218
	v_fma_f32 v80, v80, v197, v161
	v_fma_f32 v81, v81, v197, v161
	v_fma_f32 v82, v82, v197, v161
	v_fma_f32 v83, v83, v197, v161
	v_fma_f32 v84, v84, v197, v161
	v_fma_f32 v85, v85, v197, v161
	v_fma_f32 v86, v86, v197, v161
	v_fma_f32 v87, v87, v197, v161
	v_fma_f32 v88, v88, v197, v161
	v_fma_f32 v89, v89, v197, v161
	v_fma_f32 v90, v90, v197, v161
	v_fma_f32 v91, v91, v197, v161
	v_fma_f32 v92, v92, v197, v161
	v_fma_f32 v93, v93, v197, v161
	v_fma_f32 v94, v94, v197, v161
	v_fma_f32 v95, v95, v197, v161
	v_fma_f32 v174, v64, v197, v161
	v_fma_f32 v175, v65, v197, v161
	v_fma_f32 v172, v66, v197, v161
	v_fma_f32 v173, v67, v197, v161
	v_fma_f32 v170, v68, v197, v161
	v_fma_f32 v171, v69, v197, v161
	v_fma_f32 v168, v70, v197, v161
	v_fma_f32 v169, v71, v197, v161
	v_fma_f32 v166, v72, v197, v161
	v_fma_f32 v167, v73, v197, v161
	v_fma_f32 v164, v74, v197, v161
	v_fma_f32 v165, v75, v197, v161
	v_fma_f32 v162, v76, v197, v161
	v_fma_f32 v163, v77, v197, v161
	v_fma_f32 v160, v78, v197, v161
	v_fma_f32 v161, v79, v197, v161
	ds_read_b64_tr_b16 v[64:65], v226 offset:0x400
	ds_read_b64_tr_b16 v[66:67], v226 offset:0xc00
	ds_read_b64_tr_b16 v[68:69], v226 offset:0x1400
	ds_read_b64_tr_b16 v[70:71], v226 offset:0x1c00
	ds_read_b64_tr_b16 v[72:73], v226 offset:0x2400
	ds_read_b64_tr_b16 v[74:75], v226 offset:0x2c00
	ds_read_b64_tr_b16 v[76:77], v226 offset:0x3400
	ds_read_b64_tr_b16 v[78:79], v226 offset:0x3c00
	s_setprio 1
	s_waitcnt lgkmcnt(6)
	v_mfma_f32_32x32x16_bf16 v[16:31], v[112:115], v[64:67], v[16:31]
	ds_read_b64_tr_b16 v[64:65], v226 offset:0x600
	ds_read_b64_tr_b16 v[66:67], v226 offset:0xe00
	s_waitcnt lgkmcnt(6)
	v_mfma_f32_32x32x16_bf16 v[16:31], v[116:119], v[68:71], v[16:31]
	ds_read_b64_tr_b16 v[68:69], v226 offset:0x1600
	ds_read_b64_tr_b16 v[70:71], v226 offset:0x1e00
	s_waitcnt lgkmcnt(6)
	v_mfma_f32_32x32x16_bf16 v[16:31], v[120:123], v[72:75], v[16:31]
	ds_read_b64_tr_b16 v[72:73], v226 offset:0x2600
	ds_read_b64_tr_b16 v[74:75], v226 offset:0x2e00
	s_waitcnt lgkmcnt(6)
	v_mfma_f32_32x32x16_bf16 v[16:31], v[124:127], v[76:79], v[16:31]
	ds_read_b64_tr_b16 v[76:77], v226 offset:0x3600
	ds_read_b64_tr_b16 v[78:79], v226 offset:0x3e00
	s_setprio 0
	s_setprio 0
	s_waitcnt vmcnt(0) lgkmcnt(0)
	s_barrier
	s_cmp_gt_u32 s74, 28
	s_cselect_b64 s[48:49], -1, 0
	s_and_b64 vcc, exec, s[48:49]
	s_cbranch_vccnz .Lpv3_skip_a
	s_add_i32 s77, s77, s33
	s_setprio 1
	v_mfma_f32_32x32x16_bf16 v[0:15], v[112:115], v[64:67], v[0:15]
	s_add_i32 m0, s77, 0xc000
	s_add_i32 s75, s51, s75
	v_lshl_add_u64 v[64:65], v[176:177], 0, s[14:15]
	global_load_lds_dwordx4 v[64:65], off
	v_mfma_f32_32x32x16_bf16 v[0:15], v[116:119], v[68:71], v[0:15]
	v_lshl_add_u64 v[64:65], v[178:179], 0, s[34:35]
	s_mov_b32 m0, s75
	s_nop 0
	global_load_lds_dwordx4 v[64:65], off
	v_mfma_f32_32x32x16_bf16 v[0:15], v[120:123], v[72:75], v[0:15]
	v_lshl_add_u64 v[64:65], v[180:181], 0, s[34:35]
	s_add_i32 m0, s75, 0x2000
	s_nop 0
	global_load_lds_dwordx4 v[64:65], off
	v_mfma_f32_32x32x16_bf16 v[0:15], v[124:127], v[76:79], v[0:15]
	s_setprio 0
	s_branch .LBB0_1037

.LBB0_1050:
	s_lshl_b32 s0, s76, 13
	s_add_i32 s40, s0, 0
	s_setprio 1
	v_add_u32_e32 v112, s40, v189
	v_add_u32_e32 v68, v112, v191
	ds_read_b128 v[64:67], v68 offset:49152
	ds_read_b128 v[68:71], v68 offset:53248
	v_add_u32_e32 v113, v112, v192
	ds_read_b128 v[228:231], v113 offset:49152
	ds_read_b128 v[232:235], v113 offset:53248
	v_add_u32_e32 v113, v112, v193
	s_waitcnt lgkmcnt(0)
	v_mfma_f32_32x32x16_bf16 v[80:95], v[64:67], v[108:111], 0
	v_add_u32_e32 v112, v112, v194
	v_mfma_f32_32x32x16_bf16 v[64:79], v[68:71], v[108:111], 0
	v_mfma_f32_32x32x16_bf16 v[80:95], v[228:231], v[104:107], v[80:95]
	v_mfma_f32_32x32x16_bf16 v[64:79], v[232:235], v[104:107], v[64:79]
	ds_read_b128 v[228:231], v113 offset:49152
	ds_read_b128 v[232:235], v113 offset:53248
	s_waitcnt lgkmcnt(0)
	v_mfma_f32_32x32x16_bf16 v[80:95], v[228:231], v[100:103], v[80:95]
	v_mfma_f32_32x32x16_bf16 v[64:79], v[232:235], v[100:103], v[64:79]
	ds_read_b128 v[228:231], v112 offset:49152
	ds_read_b128 v[232:235], v112 offset:53248
	s_waitcnt lgkmcnt(0)
	v_mfma_f32_32x32x16_bf16 v[80:95], v[228:231], v[96:99], v[80:95]
	v_mfma_f32_32x32x16_bf16 v[64:79], v[232:235], v[96:99], v[64:79]
	s_setprio 0
	v_exp_f32_e32 v163, v180
	v_exp_f32_e32 v164, v181
	v_add_f32_e32 v112, v115, v163
	v_add_f32_e32 v113, v124, v164
	v_exp_f32_e32 v165, v178
	v_add_f32_e32 v112, v112, v125
	v_add_f32_e32 v113, v113, v126
	v_exp_f32_e32 v178, v179
	v_add_f32_e32 v112, v112, v165
	v_add_f32_e32 v113, v113, v178
	v_exp_f32_e32 v176, v176
	v_add_f32_e32 v112, v112, v127
	v_add_f32_e32 v113, v113, v160
	v_exp_f32_e32 v177, v177
	v_add_f32_e32 v112, v112, v176
	v_add_f32_e32 v113, v113, v177
	v_exp_f32_e32 v174, v174
	v_add_f32_e32 v112, v112, v161
	v_add_f32_e32 v113, v113, v162
	v_exp_f32_e32 v175, v175
	v_add_f32_e32 v112, v112, v174
	v_add_f32_e32 v113, v113, v175
	v_exp_f32_e32 v172, v172
	v_add_f32_e32 v112, v112, v116
	v_add_f32_e32 v113, v113, v117
	v_exp_f32_e32 v173, v173
	v_add_f32_e32 v112, v112, v172
	v_add_f32_e32 v113, v113, v173
	v_exp_f32_e32 v170, v170
	v_add_f32_e32 v112, v112, v118
	v_add_f32_e32 v113, v113, v119
	v_exp_f32_e32 v171, v171
	v_add_f32_e32 v112, v112, v170
	v_add_f32_e32 v113, v113, v171
	v_exp_f32_e32 v168, v168
	v_add_f32_e32 v112, v112, v120
	v_add_f32_e32 v113, v113, v121
	v_exp_f32_e32 v169, v169
	v_exp_f32_e32 v166, v166
	v_exp_f32_e32 v167, v167
	v_add_f32_e32 v112, v112, v168
	v_add_f32_e32 v113, v113, v169
	s_nop 0
	v_add_f32_e32 v112, v112, v122
	v_add_f32_e32 v113, v113, v123
	s_nop 0
	v_add_f32_e32 v112, v112, v166
	v_add_f32_e32 v113, v113, v167
	s_nop 0
	v_add_f32_e32 v225, v112, v113
	v_cvt_pk_bf16_f32 v112, v115, v124
	v_cvt_pk_bf16_f32 v113, v125, v126
	v_cvt_pk_bf16_f32 v114, v127, v160
	v_cvt_pk_bf16_f32 v115, v161, v162
	v_cvt_pk_bf16_f32 v116, v116, v117
	s_nop 0
	v_mov_b32_e32 v226, v225
	s_nop 1
	v_permlane32_swap_b32_e32 v225, v226
	v_cvt_pk_bf16_f32 v117, v118, v119
	v_cvt_pk_bf16_f32 v118, v120, v121
	v_cvt_pk_bf16_f32 v119, v122, v123
	v_cvt_pk_bf16_f32 v120, v163, v164
	v_cvt_pk_bf16_f32 v121, v165, v178
	v_cvt_pk_bf16_f32 v122, v176, v177
	v_cvt_pk_bf16_f32 v123, v174, v175
	v_cvt_pk_bf16_f32 v124, v172, v173
	v_cvt_pk_bf16_f32 v125, v170, v171
	v_cvt_pk_bf16_f32 v126, v168, v169
	v_cvt_pk_bf16_f32 v127, v166, v167
	v_permlane32_swap_b32_e32 v112, v114
	v_permlane32_swap_b32_e32 v113, v115
	v_permlane32_swap_b32_e32 v116, v118
	v_permlane32_swap_b32_e32 v117, v119
	v_permlane32_swap_b32_e32 v120, v122
	v_permlane32_swap_b32_e32 v121, v123
	v_permlane32_swap_b32_e32 v124, v126
	v_permlane32_swap_b32_e32 v125, v127
	s_lshl_b32 s0, s36, 14
	v_add_u32_e32 v230, s0, v187
	ds_read_b64_tr_b16 v[160:161], v230 offset:0
	ds_read_b64_tr_b16 v[162:163], v230 offset:0x800
	ds_read_b64_tr_b16 v[164:165], v230 offset:0x1000
	ds_read_b64_tr_b16 v[166:167], v230 offset:0x1800
	ds_read_b64_tr_b16 v[168:169], v230 offset:0x2000
	ds_read_b64_tr_b16 v[170:171], v230 offset:0x2800
	ds_read_b64_tr_b16 v[172:173], v230 offset:0x3000
	ds_read_b64_tr_b16 v[174:175], v230 offset:0x3800
	s_setprio 1
	s_waitcnt lgkmcnt(6)
	v_mfma_f32_32x32x16_bf16 v[48:63], v[112:115], v[160:163], v[48:63]
	s_waitcnt lgkmcnt(4)
	v_mfma_f32_32x32x16_bf16 v[48:63], v[116:119], v[164:167], v[48:63]
	s_waitcnt lgkmcnt(2)
	v_mfma_f32_32x32x16_bf16 v[48:63], v[120:123], v[168:171], v[48:63]
	s_waitcnt lgkmcnt(0)
	v_mfma_f32_32x32x16_bf16 v[48:63], v[124:127], v[172:175], v[48:63]
	s_setprio 0
	v_max3_f32 v160, v80, v81, v82
	v_max3_f32 v161, v64, v65, v66
	v_max_f32_e32 v162, v79, v79
	v_max3_f32 v160, v160, v83, v84
	v_max3_f32 v161, v161, v67, v68
	v_max_f32_e32 v163, v95, v95
	v_max3_f32 v160, v160, v85, v86
	v_max3_f32 v161, v161, v69, v70
	v_max_f32_e32 v162, v163, v162
	v_max3_f32 v160, v160, v87, v88
	v_max3_f32 v161, v161, v71, v72
	s_nop 0
	v_max3_f32 v160, v160, v89, v90
	v_max3_f32 v161, v161, v73, v74
	s_nop 0
	v_max3_f32 v160, v160, v91, v92
	v_max3_f32 v161, v161, v75, v76
	s_nop 0
	v_max3_f32 v160, v160, v93, v94
	v_max3_f32 v161, v161, v77, v78
	s_nop 0
	v_max3_f32 v160, v160, v161, v162
	s_nop 0
	v_mov_b32_e32 v161, v160
	s_nop 1
	v_permlane32_swap_b32_e32 v160, v161
	v_max_f32_e32 v161, v161, v161
	v_max_f32_e32 v160, v160, v160
	v_max_f32_e32 v176, v160, v161
	ds_read_b64_tr_b16 v[160:161], v230 offset:0x200
	ds_read_b64_tr_b16 v[162:163], v230 offset:0xa00
	ds_read_b64_tr_b16 v[164:165], v230 offset:0x1200
	ds_read_b64_tr_b16 v[166:167], v230 offset:0x1a00
	ds_read_b64_tr_b16 v[168:169], v230 offset:0x2200
	ds_read_b64_tr_b16 v[170:171], v230 offset:0x2a00
	ds_read_b64_tr_b16 v[172:173], v230 offset:0x3200
	ds_read_b64_tr_b16 v[174:175], v230 offset:0x3a00
	s_setprio 1
	s_waitcnt lgkmcnt(6)
	v_mfma_f32_32x32x16_bf16 v[32:47], v[112:115], v[160:163], v[32:47]
	s_waitcnt lgkmcnt(4)
	v_mfma_f32_32x32x16_bf16 v[32:47], v[116:119], v[164:167], v[32:47]
	s_waitcnt lgkmcnt(2)
	v_mfma_f32_32x32x16_bf16 v[32:47], v[120:123], v[168:171], v[32:47]
	s_waitcnt lgkmcnt(0)
	v_mfma_f32_32x32x16_bf16 v[32:47], v[124:127], v[172:175], v[32:47]
	s_setprio 0
	v_sub_f32_e32 v160, v176, v227
	v_cmp_ge_f32_e32 vcc, s71, v160
	v_max_f32_e32 v160, v227, v227
	v_max_f32_e32 v160, v160, v176
	v_sub_f32_e32 v161, v227, v160
	v_mul_f32_e32 v161, 0x3e38aa3b, v161
	v_exp_f32_e32 v161, v161
	s_cmp_eq_u64 vcc, exec
	s_cselect_b64 vcc, -1, 0
	v_cndmask_b32_e32 v229, v160, v227, vcc
	v_cndmask_b32_e64 v228, v161, 1.0, vcc
	v_mul_f32_e32 v160, 0xbe38aa3b, v229
	v_fma_f32 v80, v80, v197, v160
	v_fma_f32 v81, v81, v197, v160
	v_fma_f32 v82, v82, v197, v160
	v_fma_f32 v83, v83, v197, v160
	v_fma_f32 v84, v84, v197, v160
	v_fma_f32 v85, v85, v197, v160
	v_fma_f32 v86, v86, v197, v160
	v_fma_f32 v87, v87, v197, v160
	v_fma_f32 v88, v88, v197, v160
	v_fma_f32 v89, v89, v197, v160
	v_fma_f32 v90, v90, v197, v160
	v_fma_f32 v91, v91, v197, v160
	v_fma_f32 v92, v92, v197, v160
	v_fma_f32 v93, v93, v197, v160
	v_fma_f32 v94, v94, v197, v160
	v_fma_f32 v95, v95, v197, v160
	v_fma_f32 v166, v64, v197, v160
	v_fma_f32 v167, v65, v197, v160
	v_fma_f32 v168, v66, v197, v160
	v_fma_f32 v169, v67, v197, v160
	v_fma_f32 v170, v68, v197, v160
	v_fma_f32 v171, v69, v197, v160
	v_fma_f32 v172, v70, v197, v160
	v_fma_f32 v173, v71, v197, v160
	v_fma_f32 v174, v72, v197, v160
	v_fma_f32 v175, v73, v197, v160
	v_fma_f32 v176, v74, v197, v160
	v_fma_f32 v177, v75, v197, v160
	v_fma_f32 v178, v76, v197, v160
	v_fma_f32 v179, v77, v197, v160
	v_fma_f32 v180, v78, v197, v160
	v_fma_f32 v181, v79, v197, v160
	ds_read_b64_tr_b16 v[64:65], v230 offset:0x400
	ds_read_b64_tr_b16 v[66:67], v230 offset:0xc00
	ds_read_b64_tr_b16 v[68:69], v230 offset:0x1400
	ds_read_b64_tr_b16 v[70:71], v230 offset:0x1c00
	ds_read_b64_tr_b16 v[72:73], v230 offset:0x2400
	ds_read_b64_tr_b16 v[74:75], v230 offset:0x2c00
	ds_read_b64_tr_b16 v[76:77], v230 offset:0x3400
	ds_read_b64_tr_b16 v[78:79], v230 offset:0x3c00
	s_setprio 1
	s_waitcnt lgkmcnt(6)
	v_mfma_f32_32x32x16_bf16 v[16:31], v[112:115], v[64:67], v[16:31]
	ds_read_b64_tr_b16 v[64:65], v230 offset:0x600
	ds_read_b64_tr_b16 v[66:67], v230 offset:0xe00
	s_waitcnt lgkmcnt(6)
	v_mfma_f32_32x32x16_bf16 v[16:31], v[116:119], v[68:71], v[16:31]
	ds_read_b64_tr_b16 v[68:69], v230 offset:0x1600
	ds_read_b64_tr_b16 v[70:71], v230 offset:0x1e00
	s_waitcnt lgkmcnt(6)
	v_mfma_f32_32x32x16_bf16 v[16:31], v[120:123], v[72:75], v[16:31]
	ds_read_b64_tr_b16 v[72:73], v230 offset:0x2600
	ds_read_b64_tr_b16 v[74:75], v230 offset:0x2e00
	s_waitcnt lgkmcnt(6)
	v_mfma_f32_32x32x16_bf16 v[16:31], v[124:127], v[76:79], v[16:31]
	ds_read_b64_tr_b16 v[76:77], v230 offset:0x3600
	ds_read_b64_tr_b16 v[78:79], v230 offset:0x3e00
	s_setprio 0
	s_setprio 0
	s_lshl_b32 s1, s36, 13
	v_lshl_add_u64 v[160:161], s[64:65], 0, v[154:155]
	s_add_i32 s1, s75, s1
	s_waitcnt vmcnt(0) lgkmcnt(0)
	s_barrier
	s_setprio 1
	v_mfma_f32_32x32x16_bf16 v[0:15], v[112:115], v[64:67], v[0:15]
	v_lshl_add_u64 v[232:233], v[160:161], 0, s[58:59]
	s_add_i32 m0, s1, 0xc000
	v_lshl_add_u64 v[162:163], s[64:65], 0, v[156:157]
	s_add_i32 s0, s75, s0
	global_load_lds_dwordx4 v[232:233], off
	v_mfma_f32_32x32x16_bf16 v[0:15], v[116:119], v[68:71], v[0:15]
	v_lshl_add_u64 v[232:233], v[162:163], 0, s[10:11]
	s_mov_b32 m0, s0
	v_lshl_add_u64 v[164:165], s[64:65], 0, v[158:159]
	global_load_lds_dwordx4 v[232:233], off
	v_mfma_f32_32x32x16_bf16 v[0:15], v[120:123], v[72:75], v[0:15]
	v_lshl_add_u64 v[232:233], v[164:165], 0, s[10:11]
	s_add_i32 m0, s0, 0x2000
	v_cmp_gt_f32_e32 vcc, 1.0, v228
	global_load_lds_dwordx4 v[232:233], off
	v_mfma_f32_32x32x16_bf16 v[0:15], v[124:127], v[76:79], v[0:15]
	s_setprio 0
	s_cbranch_vccz .LBB0_1054
	s_and_saveexec_b64 s[0:1], s[4:5]
	ds_write_b32 v223, v228 offset:128
	s_or_b64 exec, exec, s[0:1]
	s_waitcnt lgkmcnt(0)
	v_add_u32_e32 v76, s33, v188
	ds_read_b128 v[64:67], v76 offset:224
	ds_read_b128 v[68:71], v76 offset:192
	ds_read_b128 v[72:75], v76 offset:160
	ds_read_b128 v[76:79], v76 offset:128
	s_waitcnt lgkmcnt(0)
	v_pk_mul_f32 v[60:61], v[60:61], v[64:65]
	v_pk_mul_f32 v[56:57], v[56:57], v[68:69]
	v_pk_mul_f32 v[52:53], v[52:53], v[72:73]
	v_pk_mul_f32 v[62:63], v[62:63], v[66:67]
	v_pk_mul_f32 v[58:59], v[58:59], v[70:71]
	v_pk_mul_f32 v[54:55], v[54:55], v[74:75]
	v_pk_mul_f32 v[50:51], v[50:51], v[78:79]
	v_pk_mul_f32 v[48:49], v[48:49], v[76:77]
	v_pk_mul_f32 v[44:45], v[44:45], v[64:65]
	v_pk_mul_f32 v[40:41], v[40:41], v[68:69]
	v_pk_mul_f32 v[36:37], v[36:37], v[72:73]
	v_pk_mul_f32 v[46:47], v[46:47], v[66:67]
	v_pk_mul_f32 v[42:43], v[42:43], v[70:71]
	v_pk_mul_f32 v[38:39], v[38:39], v[74:75]
	v_pk_mul_f32 v[34:35], v[34:35], v[78:79]
	v_pk_mul_f32 v[32:33], v[32:33], v[76:77]
	v_pk_mul_f32 v[28:29], v[28:29], v[64:65]
	v_pk_mul_f32 v[24:25], v[24:25], v[68:69]
	v_pk_mul_f32 v[20:21], v[20:21], v[72:73]
	v_pk_mul_f32 v[30:31], v[30:31], v[66:67]
	v_pk_mul_f32 v[26:27], v[26:27], v[70:71]
	v_pk_mul_f32 v[22:23], v[22:23], v[74:75]
	v_pk_mul_f32 v[18:19], v[18:19], v[78:79]
	v_pk_mul_f32 v[16:17], v[16:17], v[76:77]
	v_pk_mul_f32 v[12:13], v[12:13], v[64:65]
	v_pk_mul_f32 v[8:9], v[8:9], v[68:69]
	v_pk_mul_f32 v[4:5], v[4:5], v[72:73]
	v_pk_mul_f32 v[14:15], v[14:15], v[66:67]
	v_pk_mul_f32 v[10:11], v[10:11], v[70:71]
	v_pk_mul_f32 v[6:7], v[6:7], v[74:75]
	v_pk_mul_f32 v[2:3], v[2:3], v[78:79]
	v_pk_mul_f32 v[0:1], v[0:1], v[76:77]
.LBB0_1054:
	v_exp_f32_e32 v227, v88
	v_exp_f32_e32 v232, v89
	s_add_i32 s0, s76, 1
	s_cmp_lg_u32 s76, 2
	s_cselect_b32 s36, s0, 0
	v_exp_f32_e32 v120, v80
	v_exp_f32_e32 v121, v81
	v_exp_f32_e32 v122, v82
	v_exp_f32_e32 v123, v83
	v_exp_f32_e32 v124, v84
	v_exp_f32_e32 v125, v85
	v_exp_f32_e32 v126, v86
	v_exp_f32_e32 v127, v87
	v_exp_f32_e32 v233, v90
	v_exp_f32_e32 v234, v91
	v_exp_f32_e32 v235, v92
	v_exp_f32_e32 v236, v93
	v_exp_f32_e32 v237, v94
	v_exp_f32_e32 v238, v95
	s_setprio 1
	v_lshl_add_u32 v230, s36, 13, v190
	v_add_u32_e32 v68, v230, v191
	ds_read_b128 v[64:67], v68 offset:49152
	ds_read_b128 v[68:71], v68 offset:53248
	v_add_u32_e32 v116, v230, v192
	ds_read_b128 v[112:115], v116 offset:49152
	ds_read_b128 v[116:119], v116 offset:53248
	s_waitcnt lgkmcnt(0)
	v_mfma_f32_32x32x16_bf16 v[80:95], v[64:67], v[108:111], 0
	v_mfma_f32_32x32x16_bf16 v[64:79], v[68:71], v[108:111], 0
	v_mfma_f32_32x32x16_bf16 v[80:95], v[112:115], v[104:107], v[80:95]
	v_mfma_f32_32x32x16_bf16 v[64:79], v[116:119], v[104:107], v[64:79]
	v_add_u32_e32 v116, v230, v193
	ds_read_b128 v[112:115], v116 offset:49152
	ds_read_b128 v[116:119], v116 offset:53248
	s_waitcnt lgkmcnt(0)
	v_mfma_f32_32x32x16_bf16 v[80:95], v[112:115], v[100:103], v[80:95]
	v_mfma_f32_32x32x16_bf16 v[64:79], v[116:119], v[100:103], v[64:79]
	v_add_u32_e32 v116, v230, v194
	ds_read_b128 v[112:115], v116 offset:49152
	ds_read_b128 v[116:119], v116 offset:53248
	s_waitcnt lgkmcnt(0)
	v_mfma_f32_32x32x16_bf16 v[80:95], v[112:115], v[96:99], v[80:95]
	v_mfma_f32_32x32x16_bf16 v[64:79], v[116:119], v[96:99], v[64:79]
	s_setprio 0
	v_exp_f32_e32 v166, v166
	v_exp_f32_e32 v167, v167
	v_add_f32_e32 v112, v120, v166
	v_add_f32_e32 v113, v121, v167
	v_exp_f32_e32 v168, v168
	v_add_f32_e32 v112, v112, v122
	v_add_f32_e32 v113, v113, v123
	v_exp_f32_e32 v169, v169
	v_add_f32_e32 v112, v112, v168
	v_add_f32_e32 v113, v113, v169
	v_exp_f32_e32 v170, v170
	v_add_f32_e32 v112, v112, v124
	v_add_f32_e32 v113, v113, v125
	v_exp_f32_e32 v171, v171
	v_add_f32_e32 v112, v112, v170
	v_add_f32_e32 v113, v113, v171
	v_exp_f32_e32 v172, v172
	v_add_f32_e32 v112, v112, v126
	v_add_f32_e32 v113, v113, v127
	v_exp_f32_e32 v173, v173
	v_add_f32_e32 v112, v112, v172
	v_add_f32_e32 v113, v113, v173
	v_exp_f32_e32 v174, v174
	v_add_f32_e32 v112, v112, v227
	v_add_f32_e32 v113, v113, v232
	v_exp_f32_e32 v175, v175
	v_add_f32_e32 v112, v112, v174
	v_add_f32_e32 v113, v113, v175
	v_exp_f32_e32 v176, v176
	v_add_f32_e32 v112, v112, v233
	v_add_f32_e32 v113, v113, v234
	v_exp_f32_e32 v177, v177
	v_add_f32_e32 v112, v112, v176
	v_add_f32_e32 v113, v113, v177
	v_exp_f32_e32 v178, v178
	v_add_f32_e32 v112, v112, v235
	v_add_f32_e32 v113, v113, v236
	v_exp_f32_e32 v179, v179
	v_exp_f32_e32 v180, v180
	v_exp_f32_e32 v181, v181
	v_add_f32_e32 v112, v112, v178
	v_add_f32_e32 v113, v113, v179
	s_nop 0
	v_add_f32_e32 v112, v112, v237
	v_add_f32_e32 v113, v113, v238
	s_nop 0
	v_add_f32_e32 v112, v112, v180
	v_add_f32_e32 v113, v113, v181
	s_nop 0
	v_add_f32_e32 v230, v112, v113
	v_cvt_pk_bf16_f32 v112, v120, v121
	v_cvt_pk_bf16_f32 v113, v122, v123
	v_cvt_pk_bf16_f32 v114, v124, v125
	v_cvt_pk_bf16_f32 v115, v126, v127
	v_cvt_pk_bf16_f32 v116, v227, v232
	s_nop 0
	v_mov_b32_e32 v231, v230
	s_nop 1
	v_permlane32_swap_b32_e32 v230, v231
	v_cvt_pk_bf16_f32 v117, v233, v234
	v_cvt_pk_bf16_f32 v118, v235, v236
	v_cvt_pk_bf16_f32 v119, v237, v238
	v_cvt_pk_bf16_f32 v120, v166, v167
	v_cvt_pk_bf16_f32 v121, v168, v169
	v_cvt_pk_bf16_f32 v122, v170, v171
	v_cvt_pk_bf16_f32 v123, v172, v173
	v_cvt_pk_bf16_f32 v124, v174, v175
	v_cvt_pk_bf16_f32 v125, v176, v177
	v_cvt_pk_bf16_f32 v126, v178, v179
	v_cvt_pk_bf16_f32 v127, v180, v181
	v_permlane32_swap_b32_e32 v112, v114
	v_permlane32_swap_b32_e32 v113, v115
	v_permlane32_swap_b32_e32 v116, v118
	v_permlane32_swap_b32_e32 v117, v119
	v_permlane32_swap_b32_e32 v120, v122
	v_permlane32_swap_b32_e32 v121, v123
	v_permlane32_swap_b32_e32 v124, v126
	v_permlane32_swap_b32_e32 v125, v127
	s_lshl_b32 s41, s76, 14
	v_add_u32_e32 v233, s41, v187
	ds_read_b64_tr_b16 v[166:167], v233 offset:0
	ds_read_b64_tr_b16 v[168:169], v233 offset:0x800
	ds_read_b64_tr_b16 v[170:171], v233 offset:0x1000
	ds_read_b64_tr_b16 v[172:173], v233 offset:0x1800
	ds_read_b64_tr_b16 v[174:175], v233 offset:0x2000
	ds_read_b64_tr_b16 v[176:177], v233 offset:0x2800
	ds_read_b64_tr_b16 v[178:179], v233 offset:0x3000
	ds_read_b64_tr_b16 v[180:181], v233 offset:0x3800
	s_setprio 1
	s_waitcnt lgkmcnt(6)
	v_mfma_f32_32x32x16_bf16 v[48:63], v[112:115], v[166:169], v[48:63]
	s_waitcnt lgkmcnt(4)
	v_mfma_f32_32x32x16_bf16 v[48:63], v[116:119], v[170:173], v[48:63]
	s_waitcnt lgkmcnt(2)
	v_mfma_f32_32x32x16_bf16 v[48:63], v[120:123], v[174:177], v[48:63]
	s_waitcnt lgkmcnt(0)
	v_mfma_f32_32x32x16_bf16 v[48:63], v[124:127], v[178:181], v[48:63]
	s_setprio 0
	v_max3_f32 v166, v80, v81, v82
	v_max3_f32 v167, v64, v65, v66
	v_max_f32_e32 v168, v79, v79
	v_max3_f32 v166, v166, v83, v84
	v_max3_f32 v167, v167, v67, v68
	v_max_f32_e32 v169, v95, v95
	v_max3_f32 v166, v166, v85, v86
	v_max3_f32 v167, v167, v69, v70
	v_max_f32_e32 v168, v169, v168
	v_max3_f32 v166, v166, v87, v88
	v_max3_f32 v167, v167, v71, v72
	s_nop 0
	v_max3_f32 v166, v166, v89, v90
	v_max3_f32 v167, v167, v73, v74
	s_nop 0
	v_max3_f32 v166, v166, v91, v92
	v_max3_f32 v167, v167, v75, v76
	s_nop 0
	v_max3_f32 v166, v166, v93, v94
	v_max3_f32 v167, v167, v77, v78
	s_nop 0
	v_max3_f32 v166, v166, v167, v168
	s_nop 0
	v_mov_b32_e32 v167, v166
	s_nop 1
	v_permlane32_swap_b32_e32 v166, v167
	v_max_f32_e32 v167, v167, v167
	v_max_f32_e32 v166, v166, v166
	v_max_f32_e32 v227, v166, v167
	ds_read_b64_tr_b16 v[166:167], v233 offset:0x200
	ds_read_b64_tr_b16 v[168:169], v233 offset:0xa00
	ds_read_b64_tr_b16 v[170:171], v233 offset:0x1200
	ds_read_b64_tr_b16 v[172:173], v233 offset:0x1a00
	ds_read_b64_tr_b16 v[174:175], v233 offset:0x2200
	ds_read_b64_tr_b16 v[176:177], v233 offset:0x2a00
	ds_read_b64_tr_b16 v[178:179], v233 offset:0x3200
	ds_read_b64_tr_b16 v[180:181], v233 offset:0x3a00
	s_setprio 1
	s_waitcnt lgkmcnt(6)
	v_mfma_f32_32x32x16_bf16 v[32:47], v[112:115], v[166:169], v[32:47]
	s_waitcnt lgkmcnt(4)
	v_mfma_f32_32x32x16_bf16 v[32:47], v[116:119], v[170:173], v[32:47]
	s_waitcnt lgkmcnt(2)
	v_mfma_f32_32x32x16_bf16 v[32:47], v[120:123], v[174:177], v[32:47]
	s_waitcnt lgkmcnt(0)
	v_mfma_f32_32x32x16_bf16 v[32:47], v[124:127], v[178:181], v[32:47]
	s_setprio 0
	v_sub_f32_e32 v166, v227, v229
	v_cmp_ge_f32_e32 vcc, s71, v166
	s_cmp_eq_u64 vcc, exec
	v_max_f32_e32 v166, v229, v229
	v_max_f32_e32 v232, v166, v227
	s_cselect_b64 s[0:1], -1, 0
	v_cndmask_b32_e64 v227, v232, v229, s[0:1]
	v_mul_f32_e32 v167, 0xbe38aa3b, v227
	v_fma_f32 v80, v80, v197, v167
	v_fma_f32 v81, v81, v197, v167
	v_fma_f32 v82, v82, v197, v167
	v_fma_f32 v83, v83, v197, v167
	v_fma_f32 v84, v84, v197, v167
	v_fma_f32 v85, v85, v197, v167
	v_fma_f32 v86, v86, v197, v167
	v_fma_f32 v87, v87, v197, v167
	v_fma_f32 v88, v88, v197, v167
	v_fma_f32 v89, v89, v197, v167
	v_fma_f32 v90, v90, v197, v167
	v_fma_f32 v91, v91, v197, v167
	v_fma_f32 v92, v92, v197, v167
	v_fma_f32 v93, v93, v197, v167
	v_fma_f32 v94, v94, v197, v167
	v_fma_f32 v95, v95, v197, v167
	v_fma_f32 v180, v64, v197, v167
	v_fma_f32 v181, v65, v197, v167
	v_fma_f32 v178, v66, v197, v167
	v_fma_f32 v179, v67, v197, v167
	v_fma_f32 v176, v68, v197, v167
	v_fma_f32 v177, v69, v197, v167
	v_fma_f32 v174, v70, v197, v167
	v_fma_f32 v175, v71, v197, v167
	v_fma_f32 v172, v72, v197, v167
	v_fma_f32 v173, v73, v197, v167
	v_fma_f32 v170, v74, v197, v167
	v_fma_f32 v171, v75, v197, v167
	v_fma_f32 v168, v76, v197, v167
	v_fma_f32 v169, v77, v197, v167
	v_fma_f32 v166, v78, v197, v167
	v_fma_f32 v167, v79, v197, v167
	ds_read_b64_tr_b16 v[64:65], v233 offset:0x400
	ds_read_b64_tr_b16 v[66:67], v233 offset:0xc00
	ds_read_b64_tr_b16 v[68:69], v233 offset:0x1400
	ds_read_b64_tr_b16 v[70:71], v233 offset:0x1c00
	ds_read_b64_tr_b16 v[72:73], v233 offset:0x2400
	ds_read_b64_tr_b16 v[74:75], v233 offset:0x2c00
	ds_read_b64_tr_b16 v[76:77], v233 offset:0x3400
	ds_read_b64_tr_b16 v[78:79], v233 offset:0x3c00
	s_setprio 1
	s_waitcnt lgkmcnt(6)
	v_mfma_f32_32x32x16_bf16 v[16:31], v[112:115], v[64:67], v[16:31]
	ds_read_b64_tr_b16 v[64:65], v233 offset:0x600
	ds_read_b64_tr_b16 v[66:67], v233 offset:0xe00
	s_waitcnt lgkmcnt(6)
	v_mfma_f32_32x32x16_bf16 v[16:31], v[116:119], v[68:71], v[16:31]
	ds_read_b64_tr_b16 v[68:69], v233 offset:0x1600
	ds_read_b64_tr_b16 v[70:71], v233 offset:0x1e00
	s_waitcnt lgkmcnt(6)
	v_mfma_f32_32x32x16_bf16 v[16:31], v[120:123], v[72:75], v[16:31]
	ds_read_b64_tr_b16 v[72:73], v233 offset:0x2600
	ds_read_b64_tr_b16 v[74:75], v233 offset:0x2e00
	s_waitcnt lgkmcnt(6)
	v_mfma_f32_32x32x16_bf16 v[16:31], v[124:127], v[76:79], v[16:31]
	ds_read_b64_tr_b16 v[76:77], v233 offset:0x3600
	ds_read_b64_tr_b16 v[78:79], v233 offset:0x3e00
	s_setprio 0
	s_setprio 0
	s_waitcnt vmcnt(0) lgkmcnt(0)
	s_barrier
	s_cmp_gt_u32 s37, 28
	s_cselect_b64 s[38:39], -1, 0
	s_and_b64 vcc, exec, s[38:39]
	s_cbranch_vccnz .Lpv3_skip_b
	s_add_i32 s40, s40, s74
	s_setprio 1
	v_mfma_f32_32x32x16_bf16 v[0:15], v[112:115], v[64:67], v[0:15]
	s_add_i32 m0, s40, 0xc000
	s_add_i32 s40, s75, s41
	v_lshl_add_u64 v[64:65], v[160:161], 0, s[60:61]
	global_load_lds_dwordx4 v[64:65], off
	v_mfma_f32_32x32x16_bf16 v[0:15], v[116:119], v[68:71], v[0:15]
	v_lshl_add_u64 v[64:65], v[162:163], 0, s[34:35]
	s_mov_b32 m0, s40
	s_nop 0
	global_load_lds_dwordx4 v[64:65], off
	v_mfma_f32_32x32x16_bf16 v[0:15], v[120:123], v[72:75], v[0:15]
	v_lshl_add_u64 v[64:65], v[164:165], 0, s[34:35]
	s_add_i32 m0, s40, 0x2000
	s_nop 0
	global_load_lds_dwordx4 v[64:65], off
	v_mfma_f32_32x32x16_bf16 v[0:15], v[124:127], v[76:79], v[0:15]
	s_setprio 0
	s_branch .LBB0_1056
